# GDN chain: third workgroup barrier of a chunk moved from the head of the wave-private chain math to just before the first read of the shared KT/AT tiles
# speedup vs baseline: 1.0163x; 1.0163x over previous
; #define LAS __attribute__((address_space(3)))
; __device__ __forceinline__ unsigned pk2(float lo, float hi) { const f32v2_t f = {lo, hi}; const bf16v2_t b = __builtin_convertvector(f, bf16v2_t); return __builtin_bit_cast(unsigned, b); }
; #define WAVE_SYNC() do { asm volatile("s_waitcnt lgkmcnt(0)" ::: "memory"); __builtin_amdgcn_wave_barrier(); asm volatile("" ::: "memory"); } while (0)
; #define MFMA16(a, b, c) __builtin_amdgcn_mfma_f32_16x16x32_bf16((a), (b), (c), 0, 0, 0)
; template <int MODE>
; __device__ NOINL void chain_item(const LAS Params* lp, int l, int item, bool ctx_out, LAS unsigned char* lds) {
;     ...
;         for (int dk = 0; dk < NDK; ++dk) { u32x2 pk; pk.x = pk2(Sacc[dk][0], Sacc[dk][1]); pk.y = pk2(Sacc[dk][2], Sacc[dk][3]); *(LAS u32x2*)(ST + fr * 136 + 16 * dk + 4 * fq) = pk; }
;         WAVE_SYNC();
;         f32x4 qs[4], ksm[4];
; #pragma unroll
;         for (int ct = 0; ct < 4; ++ct) { qs[ct] = (f32x4){0.f, 0.f, 0.f, 0.f}; ksm[ct] = (f32x4){0.f, 0.f, 0.f, 0.f}; }
; #pragma unroll
;         for (int ks = 0; ks < NKS; ++ks) {
;             const bf16x8 Bf = *(const LAS bf16x8*)(ST + fr * 136 + ks * 32 + fq * 8);
; #pragma unroll
;             for (int ct = 0; ct < 4; ++ct) {
;                 const bf16x8 Aq = *(const LAS bf16x8*)(Qs + (16 * ct + fr) * 136 + kcol + ks * 32 + fq * 8);
;                 qs[ct] = MFMA16(Aq, Bf, qs[ct]);
;                 if (MODE == 0) { const bf16x8 Ak = *(const LAS bf16x8*)(Ks + (16 * ct + fr) * 136 + ks * 32 + fq * 8); ksm[ct] = MFMA16(Ak, Bf, ksm[ct]); }
;             }
;         }
.LBB0_1141:
	s_or_b64 exec, exec, s[62:63]
	ds_write_b16 v178, v68
	v_cvt_pk_bf16_f32 v68, v28, v29
	v_cvt_pk_bf16_f32 v69, v30, v31
	v_cvt_pk_bf16_f32 v70, v40, v41
	v_cvt_pk_bf16_f32 v71, v42, v43
	ds_write2_b64 v113, v[68:69], v[70:71] offset1:4
	v_cvt_pk_bf16_f32 v68, v32, v33
	v_cvt_pk_bf16_f32 v69, v34, v35
	v_cvt_pk_bf16_f32 v70, v36, v37
	v_cvt_pk_bf16_f32 v71, v38, v39
	ds_write2_b64 v113, v[68:69], v[70:71] offset0:8 offset1:12
	v_cvt_pk_bf16_f32 v68, v56, v57
	v_cvt_pk_bf16_f32 v69, v58, v59
	v_cvt_pk_bf16_f32 v70, v52, v53
	v_cvt_pk_bf16_f32 v71, v54, v55
	ds_write2_b64 v113, v[68:69], v[70:71] offset0:16 offset1:20
	v_cvt_pk_bf16_f32 v68, v44, v45
	v_cvt_pk_bf16_f32 v69, v46, v47
	v_cvt_pk_bf16_f32 v70, v48, v49
	v_cvt_pk_bf16_f32 v71, v50, v51
	ds_write2_b64 v113, v[68:69], v[70:71] offset0:24 offset1:28
	s_waitcnt lgkmcnt(0)
	v_add_u32_e32 v119, v113, v154
	ds_read_b128 v[84:87], v119
	ds_read_b128 v[100:103], v179
	ds_read_b128 v[104:107], v179 offset:17408
	ds_read_b128 v[194:197], v179 offset:4352
	ds_read_b128 v[236:239], v179 offset:21760
	ds_read_b128 v[240:243], v179 offset:8704
	ds_read_b128 v[244:247], v179 offset:26112
	ds_read_b128 v[248:251], v179 offset:13056
	v_add_u32_e32 v121, 0x25500, v110
	s_waitcnt lgkmcnt(6)
	v_mfma_f32_16x16x32_bf16 v[96:99], v[100:103], v[84:87], 0
	ds_read_b128 v[100:103], v179 offset:30464
	ds_read_b128 v[88:91], v119 offset:64
	s_add_i32 s5, s4, 4
	s_waitcnt lgkmcnt(7)
	v_mfma_f32_16x16x32_bf16 v[198:201], v[104:107], v[84:87], 0
	ds_read_b128 v[104:107], v179 offset:64
	s_and_b64 s[20:21], vcc, exec
	s_waitcnt lgkmcnt(7)
	v_mfma_f32_16x16x32_bf16 v[92:95], v[194:197], v[84:87], 0
	ds_read_b128 v[194:197], v179 offset:17472
	s_cselect_b32 s5, s1, s5
	s_waitcnt lgkmcnt(7)
	v_mfma_f32_16x16x32_bf16 v[232:235], v[236:239], v[84:87], 0
	ds_read_b128 v[236:239], v179 offset:4416
	s_add_i32 s22, s4, 40
	s_waitcnt lgkmcnt(7)
	v_mfma_f32_16x16x32_bf16 v[80:83], v[240:243], v[84:87], 0
	ds_read_b128 v[240:243], v179 offset:21824
	s_and_b64 s[20:21], vcc, exec
	s_waitcnt lgkmcnt(7)
	v_mfma_f32_16x16x32_bf16 v[72:75], v[244:247], v[84:87], 0
	ds_read_b128 v[244:247], v179 offset:8768
	s_cselect_b32 s20, s1, s22
	s_waitcnt lgkmcnt(7)
	v_mfma_f32_16x16x32_bf16 v[76:79], v[248:251], v[84:87], 0
	ds_read_b128 v[248:251], v179 offset:26176
	s_cmp_lt_u32 s1, 4
	s_waitcnt lgkmcnt(7)
	v_mfma_f32_16x16x32_bf16 v[68:71], v[100:103], v[84:87], 0
	ds_read_b128 v[100:103], v179 offset:13120
	s_cselect_b32 s1, s5, s20
	s_waitcnt lgkmcnt(6)
	v_mfma_f32_16x16x32_bf16 v[96:99], v[104:107], v[88:91], v[96:99]
	ds_read_b128 v[104:107], v179 offset:30528
	ds_read_b128 v[84:87], v119 offset:128
	s_lshl_b32 s5, s1, 6
	s_waitcnt lgkmcnt(7)
	v_mfma_f32_16x16x32_bf16 v[198:201], v[194:197], v[88:91], v[198:201]
	ds_read_b128 v[194:197], v179 offset:128
	s_add_i32 s20, s18, s5
	s_waitcnt lgkmcnt(7)
	v_mfma_f32_16x16x32_bf16 v[92:95], v[236:239], v[88:91], v[92:95]
	ds_read_b128 v[236:239], v179 offset:17536
	s_or_b32 s5, s5, s38
	s_waitcnt lgkmcnt(7)
	v_mfma_f32_16x16x32_bf16 v[232:235], v[240:243], v[88:91], v[232:235]
	ds_read_b128 v[240:243], v179 offset:4480
	s_cmp_lt_u32 s1, 4
	s_waitcnt lgkmcnt(7)
	v_mfma_f32_16x16x32_bf16 v[80:83], v[244:247], v[88:91], v[80:83]
	ds_read_b128 v[244:247], v179 offset:21888
	s_cselect_b32 s1, s5, s20
	s_waitcnt lgkmcnt(7)
	v_mfma_f32_16x16x32_bf16 v[72:75], v[248:251], v[88:91], v[72:75]
	ds_read_b128 v[248:251], v179 offset:8832
	s_mul_hi_i32 s21, s1, s19
	s_waitcnt lgkmcnt(7)
	v_mfma_f32_16x16x32_bf16 v[76:79], v[100:103], v[88:91], v[76:79]
	ds_read_b128 v[100:103], v179 offset:26240
	s_mul_i32 s20, s1, s19
	s_waitcnt lgkmcnt(7)
	v_mfma_f32_16x16x32_bf16 v[68:71], v[104:107], v[88:91], v[68:71]
	ds_read_b128 v[104:107], v179 offset:13184
	v_mov_b32_e32 v123, v1
	s_waitcnt lgkmcnt(6)
	v_mfma_f32_16x16x32_bf16 v[96:99], v[194:197], v[84:87], v[96:99]
	ds_read_b128 v[194:197], v179 offset:30592
	ds_read_b128 v[88:91], v119 offset:192
	v_add_u32_e32 v119, s34, v155
	v_mov_b32_e32 v125, v1
	s_waitcnt lgkmcnt(7)
	v_mfma_f32_16x16x32_bf16 v[198:201], v[236:239], v[84:87], v[198:201]
	ds_read_b128 v[236:239], v179 offset:192
	v_mov_b32_e32 v127, v1
	s_waitcnt lgkmcnt(7)
	v_mfma_f32_16x16x32_bf16 v[92:95], v[240:243], v[84:87], v[92:95]
	ds_read_b128 v[240:243], v179 offset:17600
	v_mov_b32_e32 v129, v1
	s_waitcnt lgkmcnt(7)
	v_mfma_f32_16x16x32_bf16 v[232:235], v[244:247], v[84:87], v[232:235]
	ds_read_b128 v[244:247], v179 offset:4544
	v_mov_b32_e32 v131, v1
	s_waitcnt lgkmcnt(7)
	v_mfma_f32_16x16x32_bf16 v[80:83], v[248:251], v[84:87], v[80:83]
	ds_read_b128 v[248:251], v179 offset:21952
	v_mov_b32_e32 v133, v1
	s_waitcnt lgkmcnt(7)
	v_mfma_f32_16x16x32_bf16 v[72:75], v[100:103], v[84:87], v[72:75]
	ds_read_b128 v[100:103], v179 offset:8896
	v_mov_b32_e32 v135, v1
	s_waitcnt lgkmcnt(7)
	v_mfma_f32_16x16x32_bf16 v[76:79], v[104:107], v[84:87], v[76:79]
	ds_read_b128 v[104:107], v179 offset:26304
	v_mov_b32_e32 v137, v1
	s_waitcnt lgkmcnt(7)
	v_mfma_f32_16x16x32_bf16 v[68:71], v[194:197], v[84:87], v[68:71]
	ds_read_b128 v[194:197], v179 offset:13248
	v_mov_b32_e32 v139, v1
	s_waitcnt lgkmcnt(6)
	v_mfma_f32_16x16x32_bf16 v[96:99], v[236:239], v[88:91], v[96:99]
	ds_read_b128 v[236:239], v179 offset:30656
	v_mov_b32_e32 v141, v1
	s_waitcnt lgkmcnt(6)
	v_mfma_f32_16x16x32_bf16 v[198:201], v[240:243], v[88:91], v[198:201]
	v_mov_b32_e32 v143, v1
	s_waitcnt lgkmcnt(5)
	v_mfma_f32_16x16x32_bf16 v[92:95], v[244:247], v[88:91], v[92:95]
	v_mov_b32_e32 v145, v1
	s_waitcnt lgkmcnt(4)
	v_mfma_f32_16x16x32_bf16 v[232:235], v[248:251], v[88:91], v[232:235]
	v_mov_b32_e32 v147, v1
	s_waitcnt lgkmcnt(3)
; #define LAS __attribute__((address_space(3)))
; __device__ __forceinline__ unsigned pk2(float lo, float hi) { const f32v2_t f = {lo, hi}; const bf16v2_t b = __builtin_convertvector(f, bf16v2_t); return __builtin_bit_cast(unsigned, b); }
; __device__ __forceinline__ float bflo(unsigned u) { return __uint_as_float(u << 16); }
; __device__ __forceinline__ float bfhi(unsigned u) { return __uint_as_float(u & 0xFFFF0000u); }
; #define MFMA16(a, b, c) __builtin_amdgcn_mfma_f32_16x16x32_bf16((a), (b), (c), 0, 0, 0)
; template <int MODE>
; __device__ NOINL void chain_item(const LAS Params* lp, int l, int item, bool ctx_out, LAS unsigned char* lds) {
;     ...
;         float eg[4][4];
; #pragma unroll
;         for (int ct = 0; ct < 4; ++ct)
; #pragma unroll
;             for (int j = 0; j < 4; ++j) { const int c = 16 * ct + 4 * fq + j; eg[ct][j] = MODE == 0 ? gcs[128 + c] : __expf((float)(c + 1) * lg); }
;         bf16x8 Bv[2];
;         if (MODE == 0) {
; #pragma unroll
;             for (int ct = 0; ct < 4; ++ct) {
;                 const u32x2 vv = *(const LAS u32x2*)(VT + (dvrow + fr) * 72 + (((2 * ct + (fq >> 1)) ^ vkey) << 3) + 4 * (fq & 1));
;                 const float v4[4] = {bflo(vv.x), bfhi(vv.x), bflo(vv.y), bfhi(vv.y)};
;                 float r[4];
; #pragma unroll
;                 for (int j = 0; j < 4; ++j) r[j] = bts[16 * ct + 4 * fq + j] * (v4[j] - eg[ct][j] * ksm[ct][j]);
;                 u32x2 pk; pk.x = pk2(r[0], r[1]); pk.y = pk2(r[2], r[3]);
;                 *(LAS u32x2*)(RP + fr * 72 + 16 * ct + 4 * fq) = pk;
;             }
;             WAVE_SYNC();
;             bf16x8 Br[2];
;             Br[0] = *(const LAS bf16x8*)(RP + fr * 72 + fq * 8); Br[1] = *(const LAS bf16x8*)(RP + fr * 72 + 32 + fq * 8);
;             f32x4 vn[4];
; #pragma unroll
;             for (int ct = 0; ct < 4; ++ct) {
;                 vn[ct] = (f32x4){0.f, 0.f, 0.f, 0.f};
; #pragma unroll
;                 for (int ks = 0; ks < 2; ++ks) { const bf16x8 A = *(const LAS bf16x8*)(TT + (16 * ct + fr) * 72 + ks * 32 + fq * 8); vn[ct] = MFMA16(A, Br[ks], vn[ct]); }
;             }
;             WAVE_SYNC();
; #pragma unroll
;             for (int ct = 0; ct < 4; ++ct) { u32x2 pk; pk.x = pk2(vn[ct][0], vn[ct][1]); pk.y = pk2(vn[ct][2], vn[ct][3]); *(LAS u32x2*)(RP + fr * 72 + 16 * ct + 4 * fq) = pk; }
;             WAVE_SYNC();
	v_mfma_f32_16x16x32_bf16 v[80:83], v[100:103], v[88:91], v[80:83]
	s_add_i32 s4, s4, -1
	s_waitcnt lgkmcnt(2)
	v_mfma_f32_16x16x32_bf16 v[72:75], v[104:107], v[88:91], v[72:75]
	s_cmp_lg_u32 s0, 36
	s_waitcnt lgkmcnt(1)
	v_mfma_f32_16x16x32_bf16 v[76:79], v[194:197], v[88:91], v[76:79]
	s_mov_b32 s1, s0
	s_waitcnt lgkmcnt(0)
	v_mfma_f32_16x16x32_bf16 v[68:71], v[236:239], v[88:91], v[68:71]
	ds_read_b64 v[88:89], v186 offset:53248
	ds_read_b128 v[104:107], v119 offset:512
	ds_read_b128 v[84:87], v121
	s_waitcnt lgkmcnt(2)
	v_lshlrev_b32_e32 v90, 16, v88
	v_and_b32_e32 v91, 0xffff0000, v88
	v_lshlrev_b32_e32 v88, 16, v89
	v_and_b32_e32 v89, 0xffff0000, v89
	s_waitcnt lgkmcnt(1)
	v_pk_fma_f32 v[90:91], v[198:199], v[104:105], v[90:91] neg_lo:[1,0,0] neg_hi:[1,0,0]
	v_pk_fma_f32 v[88:89], v[200:201], v[106:107], v[88:89] neg_lo:[1,0,0] neg_hi:[1,0,0]
	s_waitcnt lgkmcnt(0)
	v_pk_mul_f32 v[84:85], v[84:85], v[90:91]
	v_pk_mul_f32 v[86:87], v[86:87], v[88:89]
	v_cvt_pk_bf16_f32 v148, v84, v85
	v_cvt_pk_bf16_f32 v149, v86, v87
	ds_read_b128 v[100:103], v119 offset:576
	ds_read_b128 v[88:91], v119 offset:640
	ds_read_b128 v[84:87], v119 offset:704
	ds_write_b64 v158, v[148:149] offset:4352
	ds_read_b64 v[148:149], v187 offset:53248
	ds_read_b128 v[194:197], v121 offset:64
	v_add_u32_e32 v119, v158, v154
	s_waitcnt lgkmcnt(1)
	v_lshlrev_b32_e32 v198, 16, v148
	v_and_b32_e32 v199, 0xffff0000, v148
	v_lshlrev_b32_e32 v148, 16, v149
	v_and_b32_e32 v149, 0xffff0000, v149
	v_pk_fma_f32 v[198:199], v[232:233], v[100:101], v[198:199] neg_lo:[1,0,0] neg_hi:[1,0,0]
	v_pk_fma_f32 v[148:149], v[234:235], v[102:103], v[148:149] neg_lo:[1,0,0] neg_hi:[1,0,0]
	s_waitcnt lgkmcnt(0)
	v_pk_mul_f32 v[194:195], v[194:195], v[198:199]
	v_pk_mul_f32 v[148:149], v[196:197], v[148:149]
	v_cvt_pk_bf16_f32 v194, v194, v195
	v_cvt_pk_bf16_f32 v195, v148, v149
	ds_write_b64 v158, v[194:195] offset:4384
	ds_read_b64 v[148:149], v188 offset:53248
	ds_read_b128 v[194:197], v121 offset:128
	s_waitcnt lgkmcnt(1)
	v_lshlrev_b32_e32 v198, 16, v148
	v_and_b32_e32 v199, 0xffff0000, v148
	v_lshlrev_b32_e32 v148, 16, v149
	v_and_b32_e32 v149, 0xffff0000, v149
	v_pk_fma_f32 v[72:73], v[72:73], v[88:89], v[198:199] neg_lo:[1,0,0] neg_hi:[1,0,0]
	v_pk_fma_f32 v[74:75], v[74:75], v[90:91], v[148:149] neg_lo:[1,0,0] neg_hi:[1,0,0]
	s_waitcnt lgkmcnt(0)
	v_pk_mul_f32 v[72:73], v[194:195], v[72:73]
	v_pk_mul_f32 v[74:75], v[196:197], v[74:75]
	v_cvt_pk_bf16_f32 v72, v72, v73
	v_cvt_pk_bf16_f32 v73, v74, v75
	ds_write_b64 v158, v[72:73] offset:4416
	ds_read_b64 v[72:73], v189 offset:53248
	s_waitcnt lgkmcnt(0)
	v_lshlrev_b32_e32 v148, 16, v72
	v_and_b32_e32 v149, 0xffff0000, v72
	v_lshlrev_b32_e32 v194, 16, v73
	v_and_b32_e32 v195, 0xffff0000, v73
	ds_read_b128 v[72:75], v121 offset:192
	v_pk_fma_f32 v[68:69], v[68:69], v[84:85], v[148:149] neg_lo:[1,0,0] neg_hi:[1,0,0]
	v_pk_fma_f32 v[70:71], v[70:71], v[86:87], v[194:195] neg_lo:[1,0,0] neg_hi:[1,0,0]
	v_add_u32_e32 v121, v159, v157
	v_lshl_add_u64 v[148:149], s[20:21], 1, v[116:117]
	s_waitcnt lgkmcnt(0)
	v_pk_mul_f32 v[68:69], v[72:73], v[68:69]
	v_pk_mul_f32 v[70:71], v[74:75], v[70:71]
	v_cvt_pk_bf16_f32 v68, v68, v69
	v_cvt_pk_bf16_f32 v69, v70, v71
	ds_write_b64 v158, v[68:69] offset:4448
	s_waitcnt lgkmcnt(0)
	ds_read_b128 v[68:71], v119 offset:4352
	ds_read_b128 v[72:75], v119 offset:4416
	ds_read_b128 v[194:197], v121
	ds_read_b128 v[198:201], v121 offset:64
	s_waitcnt lgkmcnt(1)
	v_mfma_f32_16x16x32_bf16 v[194:197], v[194:197], v[68:71], 0
	v_add_u32_e32 v121, v159, v180
	ds_read_b128 v[232:235], v121 offset:64
	ds_read_b128 v[236:239], v121 offset:2368
	s_waitcnt lgkmcnt(2)
	v_mfma_f32_16x16x32_bf16 v[194:197], v[198:201], v[72:75], v[194:197]
	ds_read_b128 v[198:201], v121
	s_waitcnt lgkmcnt(0)
	v_mfma_f32_16x16x32_bf16 v[198:201], v[198:201], v[68:71], 0
	v_mfma_f32_16x16x32_bf16 v[198:201], v[232:235], v[72:75], v[198:201]
	ds_read_b128 v[232:235], v121 offset:2304
	s_waitcnt lgkmcnt(0)
	v_mfma_f32_16x16x32_bf16 v[232:235], v[232:235], v[68:71], 0
	v_mfma_f32_16x16x32_bf16 v[232:235], v[236:239], v[72:75], v[232:235]
	ds_read_b128 v[236:239], v121 offset:4608
	s_waitcnt lgkmcnt(0)
	v_mfma_f32_16x16x32_bf16 v[68:71], v[236:239], v[68:71], 0
	ds_read_b128 v[236:239], v121 offset:4672
	v_add_u32_e32 v121, 0x1000, v158
	s_waitcnt lgkmcnt(0)
	s_waitcnt lgkmcnt(0)
	v_mfma_f32_16x16x32_bf16 v[68:71], v[236:239], v[72:75], v[68:71]
	v_cvt_pk_bf16_f32 v72, v194, v195
	v_cvt_pk_bf16_f32 v73, v196, v197
	v_cvt_pk_bf16_f32 v74, v198, v199
	v_cvt_pk_bf16_f32 v75, v200, v201
	ds_write2_b64 v121, v[72:73], v[74:75] offset0:32 offset1:36
	v_cvt_pk_bf16_f32 v72, v232, v233
	v_cvt_pk_bf16_f32 v73, v234, v235
	s_nop 0
	v_cvt_pk_bf16_f32 v68, v68, v69
	v_cvt_pk_bf16_f32 v69, v70, v71
	ds_write2_b64 v121, v[72:73], v[68:69] offset0:40 offset1:44
	s_waitcnt lgkmcnt(0)
	s_barrier
; #define LAS __attribute__((address_space(3)))
; __device__ __forceinline__ bf16_t f2bf(float f) { return (bf16_t)(pk2(f, f) & 0xFFFFu); }
; #define MFMA16(a, b, c) __builtin_amdgcn_mfma_f32_16x16x32_bf16((a), (b), (c), 0, 0, 0)
; template <int MODE>
; __device__ NOINL void chain_item(const LAS Params* lp, int l, int item, bool ctx_out, LAS unsigned char* lds) {
;     ...
;             Bv[0] = *(const LAS bf16x8*)(RP + fr * 72 + fq * 8); Bv[1] = *(const LAS bf16x8*)(RP + fr * 72 + 32 + fq * 8);
;         } else {
;             Bv[0] = *(const LAS bf16x8*)(VT + (dvrow + fr) * 72 + ((fq ^ vkey) << 3)); Bv[1] = *(const LAS bf16x8*)(VT + (dvrow + fr) * 72 + (((4 + fq) ^ vkey) << 3));
;         }
;         {
;             typedef __attribute__((address_space(1))) bf16_t gbf16;
;             bf16_t* ob; int ldo;
;             if (MODE == 0) { if (dir == 0) { ob = p.hbuf + 256 + h * 128 + 16 * w; ldo = 1024; } else { ob = p.hyproj + h * 128 + 16 * w; ldo = 768; } }
;             else { if (dir == 0) { ob = p.hbuf + 768 + (h + hh) * 64 + 16 * (w & 3); ldo = 1024; } else { ob = p.hyproj + 512 + (h + hh) * 64 + 16 * (w & 3); ldo = 768; } }
; #pragma unroll
;             for (int ct = 0; ct < 4; ++ct) {
;                 f32x4 acc = {0.f, 0.f, 0.f, 0.f};
; #pragma unroll
;                 for (int ks = 0; ks < 2; ++ks) { const bf16x8 A = *(const LAS bf16x8*)(AT + hh * 4608 + (16 * ct + fr) * 72 + ks * 32 + fq * 8); acc = MFMA16(A, Bv[ks], acc); }
;                 gbf16* og = (gbf16*)ob + (size_t)row0 * ldo + fr;
; #pragma unroll
;                 for (int j = 0; j < 4; ++j) { const int c = 16 * ct + 4 * fq + j, tok = dir ? 63 - c : c; og[tok * ldo] = f2bf(eg[ct][j] * qs[ct][j] + acc[j]); }
;             }
;         }
;         {
;             const float gl = MODE == 0 ? gcs[128 + 63] : __expf(64.f * lg);
; #pragma unroll
;             for (int dk = 0; dk < NDK; ++dk) {
;                 Sacc[dk] = Sacc[dk] * gl;
; #pragma unroll
;                 for (int ks = 0; ks < 2; ++ks) { const bf16x8 A = *(const LAS bf16x8*)(KT + (kcol + 16 * dk + fr) * 72 + (((ks * 4 + fq) ^ (((kcol >> 4) + dk) & 7)) << 3)); Sacc[dk] = MFMA16(A, Bv[ks], Sacc[dk]); }
	ds_read_b128 v[72:75], v119 offset:4352
	ds_read_b128 v[68:71], v119 offset:4416
	v_add_u32_e32 v218, v160, v157
	v_add_u32_e32 v219, v160, v180
	v_mov_b32_e32 v119, v1
	v_mov_b32_e32 v121, v1
	ds_read_b128 v[194:197], v218
	ds_read_b128 v[232:235], v219
	ds_read_b128 v[244:247], v219 offset:2304
	ds_read_b128 v[236:239], v219 offset:4608
	ds_read_b128 v[198:201], v218 offset:64
	ds_read_b128 v[240:243], v219 offset:64
	ds_read_b128 v[248:251], v219 offset:2368
	s_waitcnt lgkmcnt(6)
	v_mfma_f32_16x16x32_bf16 v[194:197], v[194:197], v[72:75], 0
	s_waitcnt lgkmcnt(5)
	v_mfma_f32_16x16x32_bf16 v[232:235], v[232:235], v[72:75], 0
	s_waitcnt lgkmcnt(4)
	v_mfma_f32_16x16x32_bf16 v[244:247], v[244:247], v[72:75], 0
	s_waitcnt lgkmcnt(3)
	v_mfma_f32_16x16x32_bf16 v[236:239], v[236:239], v[72:75], 0
	s_waitcnt lgkmcnt(2)
	v_mfma_f32_16x16x32_bf16 v[194:197], v[198:201], v[68:71], v[194:197]
	ds_read_b128 v[198:201], v219 offset:4672
	s_waitcnt lgkmcnt(2)
	v_mfma_f32_16x16x32_bf16 v[232:235], v[240:243], v[68:71], v[232:235]
	s_waitcnt lgkmcnt(1)
	v_mfma_f32_16x16x32_bf16 v[244:247], v[248:251], v[68:71], v[244:247]
	s_waitcnt lgkmcnt(0)
	v_mfma_f32_16x16x32_bf16 v[236:239], v[198:201], v[68:71], v[236:239]
	v_lshl_add_u64 v[240:241], v[148:149], 0, v[0:1]
	v_lshl_add_u64 v[242:243], v[148:149], 0, v[118:119]
	v_lshl_add_u64 v[248:249], v[148:149], 0, v[120:121]
	v_lshl_add_u64 v[250:251], v[148:149], 0, v[122:123]
	s_nop 3
	v_fma_f32 v194, v96, v104, v194
	v_fma_f32 v195, v97, v105, v195
	v_fma_f32 v196, v98, v106, v196
	v_fma_f32 v197, v99, v107, v197
	v_cvt_pk_bf16_f32 v194, v194, v194
	v_cvt_pk_bf16_f32 v195, v195, v195
	v_cvt_pk_bf16_f32 v196, v196, v196
	v_cvt_pk_bf16_f32 v197, v197, v197
	global_store_short v[240:241], v194, off
	global_store_short v[242:243], v195, off
	global_store_short v[248:249], v196, off
	global_store_short v[250:251], v197, off
	v_lshl_add_u64 v[240:241], v[148:149], 0, v[124:125]
	v_lshl_add_u64 v[242:243], v[148:149], 0, v[126:127]
	v_lshl_add_u64 v[248:249], v[148:149], 0, v[128:129]
	v_lshl_add_u64 v[250:251], v[148:149], 0, v[130:131]
	v_fma_f32 v232, v92, v100, v232
	v_fma_f32 v233, v93, v101, v233
	v_fma_f32 v234, v94, v102, v234
	v_fma_f32 v235, v95, v103, v235
	v_cvt_pk_bf16_f32 v232, v232, v232
	v_cvt_pk_bf16_f32 v233, v233, v233
	v_cvt_pk_bf16_f32 v234, v234, v234
	v_cvt_pk_bf16_f32 v235, v235, v235
	global_store_short v[240:241], v232, off
	global_store_short v[242:243], v233, off
	global_store_short v[248:249], v234, off
	global_store_short v[250:251], v235, off
	v_lshl_add_u64 v[240:241], v[148:149], 0, v[132:133]
	v_lshl_add_u64 v[242:243], v[148:149], 0, v[134:135]
	v_lshl_add_u64 v[248:249], v[148:149], 0, v[136:137]
	v_lshl_add_u64 v[250:251], v[148:149], 0, v[138:139]
	v_fma_f32 v244, v80, v88, v244
	v_fma_f32 v245, v81, v89, v245
	v_fma_f32 v246, v82, v90, v246
	v_fma_f32 v247, v83, v91, v247
	v_cvt_pk_bf16_f32 v244, v244, v244
	v_cvt_pk_bf16_f32 v245, v245, v245
	v_cvt_pk_bf16_f32 v246, v246, v246
	v_cvt_pk_bf16_f32 v247, v247, v247
	global_store_short v[240:241], v244, off
	global_store_short v[242:243], v245, off
	global_store_short v[248:249], v246, off
	global_store_short v[250:251], v247, off
	v_lshl_add_u64 v[240:241], v[148:149], 0, v[140:141]
	v_lshl_add_u64 v[242:243], v[148:149], 0, v[142:143]
	v_lshl_add_u64 v[248:249], v[148:149], 0, v[144:145]
	v_lshl_add_u64 v[250:251], v[148:149], 0, v[146:147]
	v_fma_f32 v236, v76, v84, v236
	v_fma_f32 v237, v77, v85, v237
	v_fma_f32 v238, v78, v86, v238
	v_fma_f32 v239, v79, v87, v239
	v_cvt_pk_bf16_f32 v236, v236, v236
	v_cvt_pk_bf16_f32 v237, v237, v237
	v_cvt_pk_bf16_f32 v238, v238, v238
	v_cvt_pk_bf16_f32 v239, v239, v239
	global_store_short v[240:241], v236, off
	global_store_short v[242:243], v237, off
	global_store_short v[248:249], v238, off
	global_store_short v[250:251], v239, off
	v_mov_b32_e32 v76, s17
	ds_read_b32 v76, v76
	v_add_u32_e32 v83, v161, v155
	v_add_u32_e32 v82, v181, v182
	v_add_u32_e32 v84, v161, v182
	v_add_u32_e32 v85, v161, v183
	v_add_u32_e32 v86, v161, v162
	ds_read_b128 v[88:91], v83 offset:34816
	ds_read_b128 v[92:95], v82 offset:34816
	ds_read_b128 v[96:99], v190 offset:34816
	ds_read_b128 v[100:103], v191 offset:34816
	ds_read_b128 v[104:107], v83 offset:44096
	ds_read_b128 v[194:197], v84 offset:46400
	ds_read_b128 v[198:201], v85 offset:48704
	ds_read_b128 v[232:235], v86 offset:51008
	s_waitcnt lgkmcnt(8)
; #define LAS __attribute__((address_space(3)))
; #define MFMA16(a, b, c) __builtin_amdgcn_mfma_f32_16x16x32_bf16((a), (b), (c), 0, 0, 0)
; template <int MODE>
; __device__ NOINL void chain_item(const LAS Params* lp, int l, int item, bool ctx_out, LAS unsigned char* lds) {
;     ...
;         {
;             const float gl = MODE == 0 ? gcs[128 + 63] : __expf(64.f * lg);
; #pragma unroll
;             for (int dk = 0; dk < NDK; ++dk) {
;                 Sacc[dk] = Sacc[dk] * gl;
; #pragma unroll
;                 for (int ks = 0; ks < 2; ++ks) { const bf16x8 A = *(const LAS bf16x8*)(KT + (kcol + 16 * dk + fr) * 72 + (((ks * 4 + fq) ^ (((kcol >> 4) + dk) & 7)) << 3)); Sacc[dk] = MFMA16(A, Bv[ks], Sacc[dk]); }
;             }
;         }
	v_pk_mul_f32 v[30:31], v[30:31], v[76:77] op_sel_hi:[1,0]
	v_pk_mul_f32 v[28:29], v[28:29], v[76:77] op_sel_hi:[1,0]
	v_pk_mul_f32 v[42:43], v[42:43], v[76:77] op_sel_hi:[1,0]
	v_pk_mul_f32 v[40:41], v[40:41], v[76:77] op_sel_hi:[1,0]
	v_pk_mul_f32 v[34:35], v[34:35], v[76:77] op_sel_hi:[1,0]
	v_pk_mul_f32 v[32:33], v[32:33], v[76:77] op_sel_hi:[1,0]
	v_pk_mul_f32 v[38:39], v[38:39], v[76:77] op_sel_hi:[1,0]
	v_pk_mul_f32 v[36:37], v[36:37], v[76:77] op_sel_hi:[1,0]
	v_pk_mul_f32 v[58:59], v[58:59], v[76:77] op_sel_hi:[1,0]
	v_pk_mul_f32 v[56:57], v[56:57], v[76:77] op_sel_hi:[1,0]
	v_pk_mul_f32 v[54:55], v[54:55], v[76:77] op_sel_hi:[1,0]
	v_pk_mul_f32 v[52:53], v[52:53], v[76:77] op_sel_hi:[1,0]
	v_pk_mul_f32 v[46:47], v[46:47], v[76:77] op_sel_hi:[1,0]
	v_pk_mul_f32 v[44:45], v[44:45], v[76:77] op_sel_hi:[1,0]
	v_pk_mul_f32 v[50:51], v[50:51], v[76:77] op_sel_hi:[1,0]
	v_pk_mul_f32 v[48:49], v[48:49], v[76:77] op_sel_hi:[1,0]
	s_waitcnt lgkmcnt(7)
	v_mfma_f32_16x16x32_bf16 v[28:31], v[88:91], v[72:75], v[28:31]
	ds_read_b128 v[88:91], v83 offset:34880
	s_waitcnt lgkmcnt(7)
	v_mfma_f32_16x16x32_bf16 v[40:43], v[92:95], v[72:75], v[40:43]
	ds_read_b128 v[92:95], v82 offset:34880
	s_waitcnt lgkmcnt(7)
	v_mfma_f32_16x16x32_bf16 v[32:35], v[96:99], v[72:75], v[32:35]
	ds_read_b128 v[96:99], v190 offset:34880
	s_waitcnt lgkmcnt(7)
	v_mfma_f32_16x16x32_bf16 v[36:39], v[100:103], v[72:75], v[36:39]
	ds_read_b128 v[100:103], v191 offset:34880
	s_waitcnt lgkmcnt(7)
	v_mfma_f32_16x16x32_bf16 v[56:59], v[104:107], v[72:75], v[56:59]
	ds_read_b128 v[104:107], v83 offset:44032
	s_waitcnt lgkmcnt(7)
	v_mfma_f32_16x16x32_bf16 v[52:55], v[194:197], v[72:75], v[52:55]
	ds_read_b128 v[194:197], v84 offset:46336
	s_waitcnt lgkmcnt(7)
	v_mfma_f32_16x16x32_bf16 v[44:47], v[198:201], v[72:75], v[44:47]
	ds_read_b128 v[198:201], v85 offset:48640
	s_waitcnt lgkmcnt(7)
	v_mfma_f32_16x16x32_bf16 v[48:51], v[232:235], v[72:75], v[48:51]
	ds_read_b128 v[232:235], v86 offset:50944
	s_waitcnt lgkmcnt(7)
	v_mfma_f32_16x16x32_bf16 v[28:31], v[88:91], v[68:71], v[28:31]
	s_waitcnt lgkmcnt(6)
	v_mfma_f32_16x16x32_bf16 v[40:43], v[92:95], v[68:71], v[40:43]
	s_waitcnt lgkmcnt(5)
	v_mfma_f32_16x16x32_bf16 v[32:35], v[96:99], v[68:71], v[32:35]
	s_waitcnt lgkmcnt(4)
	v_mfma_f32_16x16x32_bf16 v[36:39], v[100:103], v[68:71], v[36:39]
	s_waitcnt lgkmcnt(3)
	v_mfma_f32_16x16x32_bf16 v[56:59], v[104:107], v[68:71], v[56:59]
	s_waitcnt lgkmcnt(2)
	v_mfma_f32_16x16x32_bf16 v[52:55], v[194:197], v[68:71], v[52:55]
	s_waitcnt lgkmcnt(1)
	v_mfma_f32_16x16x32_bf16 v[44:47], v[198:201], v[68:71], v[44:47]
	s_waitcnt lgkmcnt(0)
	v_mfma_f32_16x16x32_bf16 v[48:51], v[232:235], v[68:71], v[48:51]
	s_waitcnt vmcnt(19)
	v_mov_b64_e32 v[74:75], v[66:67]
	v_mov_b64_e32 v[70:71], v[62:63]
	v_mov_b64_e32 v[72:73], v[64:65]
	v_mov_b64_e32 v[68:69], v[60:61]
	s_cbranch_scc0 .LBB0_1135
